# v59 + whole-kernel code placement shifted by 16 bytes (4 s_nop at entry), placement comparison with the 8- and 32-byte shifts
# speedup vs baseline: 1.0024x; 1.0024x over previous
_Z8mega_fwd4Args:
	s_nop 0
	s_nop 0
	s_nop 0
	s_nop 0
	s_mov_b64 s[70:71], s[0:1]
	s_load_dword s86, s[70:71], 0x128
	v_lshl_add_u32 v1, v0, 2, 0
	s_add_u32 s80, s70, 0x128
	v_add_u32_e32 v1, 0x20000, v1
	v_mov_b32_e32 v2, 0
	s_mov_b32 s82, s2
	v_readfirstlane_b32 s0, v0
	s_addc_u32 s81, s71, 0
	ds_write2st64_b32 v1, v2, v2 offset1:8
	ds_write2st64_b32 v1, v2, v2 offset0:16 offset1:24
	v_or_b32_e32 v1, 0x800, v0
	s_mov_b64 s[2:3], -1
	s_and_saveexec_b64 s[4:5], s[2:3]
	v_lshl_add_u32 v3, v1, 2, 0
	v_add_u32_e32 v3, 0x20000, v3
	ds_write_b32 v3, v2
	s_or_b64 exec, exec, s[4:5]
	s_and_saveexec_b64 s[4:5], s[2:3]
	s_add_i32 s1, 0, 0x20000
	v_lshl_add_u32 v1, v1, 2, s1
	v_mov_b32_e32 v2, 0
	ds_write_b32 v1, v2 offset:2048
	s_or_b64 exec, exec, s[4:5]
	s_load_dwordx2 s[72:73], s[70:71], 0xf8
	v_or_b32_e32 v1, 0xc00, v0
	v_cmp_gt_u32_e64 s[2:3], 7, 6
	v_cmp_gt_u32_e64 s[6:7], 7, 5
	s_and_saveexec_b64 s[4:5], s[6:7]
	v_lshl_add_u32 v2, v1, 2, 0
	v_add_u32_e32 v2, 0x20000, v2
	v_mov_b32_e32 v3, 0
	ds_write_b32 v2, v3
	s_or_b64 exec, exec, s[4:5]
	s_and_saveexec_b64 s[4:5], s[2:3]
	s_add_i32 s1, 0, 0x20000
	v_lshl_add_u32 v1, v1, 2, s1
	v_mov_b32_e32 v2, 0
	ds_write_b32 v1, v2 offset:2048
	s_or_b64 exec, exec, s[4:5]
	s_waitcnt lgkmcnt(0)
	s_barrier
	s_add_u32 s78, s72, 0x4000
	s_getreg_b32 s1, hwreg(HW_REG_XCC_ID, 0, 4)
	s_addc_u32 s79, s73, 0
	s_and_b32 s67, s1, 15
	v_cmp_eq_u32_e64 s[84:85], 0, v0
	s_and_saveexec_b64 s[2:3], s[84:85]
	s_cbranch_execz .LBB0_11
	s_mov_b64 s[4:5], exec
	v_mbcnt_lo_u32_b32 v1, s4, 0
	v_mbcnt_hi_u32_b32 v1, s5, v1
	v_cmp_eq_u32_e32 vcc, 0, v1
	s_and_b64 s[6:7], exec, vcc
	s_mov_b64 exec, s[6:7]
	s_cbranch_execz .LBB0_11
	s_lshl_b32 s1, s67, 8
	s_bcnt1_i32_b64 s4, s[4:5]
	v_mov_b32_e32 v1, s1
	v_mov_b32_e32 v2, s4
	global_atomic_add v1, v2, s[78:79] offset:1024
